# weight-convert tile loads batched (16 in flight); s5 pass-1 scan: B*u chains of two time steps interleaved, u tiles read one pair ahead
# speedup vs baseline: 1.2376x; 1.0146x over previous
; DI void s5_coef(const Params& P, int l, int g, int p, S5Coef& C) {
;   float dt = expf(P.in[13][l * 16 + g]);
;   float lr = P.in[11][(l * 16 + g) * 64 + p], li = P.in[12][(l * 16 + g) * 64 + p];
;   float mag = expf(lr * dt);
;   double s, c; sincos_d((double)(li * dt), s, c);
;   C.ar = mag * (float)c; C.ai = mag * (float)s;
;   const float inv_den = __builtin_amdgcn_rcpf(lr * lr + li * li);
;   float fr = ((C.ar - 1.f) * lr + C.ai * li) * inv_den;
;   float fi = (C.ai * lr - (C.ar - 1.f) * li) * inv_den;
.LBB0_514:
	s_and_b64 vcc, exec, s[0:1]
	s_cbranch_vccz .LBB0_518
	v_mov_b32_e32 v0, v160
	s_add_i32 s0, s16, 0xfffff7c0
	s_bfe_u32 s4, s0, 0x60002
	s_waitcnt vmcnt(7)
	v_and_b32_e32 v42, 63, v0
	v_mov_b32_e32 v0, v160
	s_lshr_b32 s5, s0, 8
	s_lshl_b32 s0, s0, 2
	s_and_b32 s0, s0, 12
	v_ashrrev_i32_e32 v1, 6, v0
	v_add_u32_e32 v0, s0, v1
	v_readlane_b32 s6, v245, 12
	v_readlane_b32 s72, v247, 23
	v_readlane_b32 s82, v247, 33
	v_add_u32_e32 v4, s6, v0
	v_ashrrev_i32_e32 v5, 31, v4
	v_readlane_b32 s83, v247, 34
	s_mov_b64 s[0:1], 0
	s_mov_b32 s6, 0x3fb8aa3b
	v_lshl_add_u64 v[2:3], v[4:5], 2, s[82:83]
	global_load_dword v3, v[2:3], off
	s_mov_b32 s7, 0xc2ce8ed0
	s_mov_b32 s8, 0x42b17218
	v_readlane_b32 s78, v247, 29
	v_readlane_b32 s79, v247, 30
	v_readlane_b32 s80, v247, 31
	v_readlane_b32 s81, v247, 32
	s_mov_b32 s10, 0x92492492
	s_mov_b32 s11, 0xbf924924
	v_readlane_b32 s84, v247, 35
	v_readlane_b32 s85, v247, 36
	v_readlane_b32 s86, v247, 37
	v_readlane_b32 s87, v247, 38
	s_add_u32 s0, s70, s0
	s_addc_u32 s1, s71, s1
	v_lshlrev_b32_e32 v1, 12, v1
	v_readlane_b32 s73, v247, 24
	v_readlane_b32 s74, v247, 25
	v_readlane_b32 s75, v247, 26
	v_readlane_b32 s76, v247, 27
	v_readlane_b32 s77, v247, 28
	s_waitcnt vmcnt(0)
	v_mul_f32_e32 v2, 0x3fb8aa3b, v3
	v_fma_f32 v6, v3, s6, -v2
	v_rndne_f32_e32 v7, v2
	v_fmac_f32_e32 v6, 0x32a5705f, v3
	v_sub_f32_e32 v2, v2, v7
	v_add_f32_e32 v2, v2, v6
	v_exp_f32_e32 v2, v2
	v_cvt_i32_f32_e32 v6, v7
	v_cmp_ngt_f32_e32 vcc, s7, v3
	v_ldexp_f32 v6, v2, v6
	s_nop 0
	v_cndmask_b32_e32 v6, 0, v6, vcc
	v_cmp_nlt_f32_e32 vcc, s8, v3
	v_mov_b32_e32 v2, 0
	s_nop 0
	v_cndmask_b32_e32 v3, v187, v6, vcc
	v_lshl_or_b32 v6, v4, 6, v42
	v_ashrrev_i32_e32 v7, 31, v6
	v_lshlrev_b64 v[6:7], 2, v[6:7]
	v_lshl_add_u64 v[8:9], s[78:79], 0, v[6:7]
	global_load_dword v8, v[8:9], off
	v_lshl_add_u64 v[6:7], s[80:81], 0, v[6:7]
	global_load_dword v9, v[6:7], off
	v_lshlrev_b64 v[4:5], 12, v[4:5]
	s_waitcnt vmcnt(1)
	v_mul_f32_e32 v6, v3, v8
	v_mul_f32_e32 v7, 0x3fb8aa3b, v6
	v_fma_f32 v10, v6, s6, -v7
	v_rndne_f32_e32 v11, v7
	v_fmac_f32_e32 v10, 0x32a5705f, v6
	v_sub_f32_e32 v7, v7, v11
	v_add_f32_e32 v7, v7, v10
	v_exp_f32_e32 v7, v7
	v_cvt_i32_f32_e32 v10, v11
	v_cmp_ngt_f32_e32 vcc, s7, v6
	s_waitcnt vmcnt(0)
	v_mul_f32_e32 v3, v3, v9
	s_mov_b32 s6, 0x6dc9c883
	v_cvt_f64_f32_e32 v[44:45], v3
	s_mov_b32 s7, 0x3fc45f30
	v_ldexp_f32 v7, v7, v10
	v_mul_f64 v[10:11], v[44:45], s[6:7]
	s_mov_b32 s6, 0x54442d18
	v_rndne_f64_e32 v[10:11], v[10:11]
	s_mov_b32 s7, 0xc01921fb
	v_fmac_f64_e32 v[44:45], s[6:7], v[10:11]
	v_mul_f64 v[46:47], v[44:45], v[44:45]
	v_mul_f64 v[20:21], v[46:47], s[10:11]
	s_mov_b32 s10, 0x16c16c17
	s_mov_b32 s11, 0xbf86c16c
	v_mul_f64 v[24:25], v[46:47], s[10:11]
	s_mov_b32 s10, 0xf07c1f08
	s_mov_b32 s11, 0xbf7f07c1
	v_mul_f64 v[28:29], v[46:47], s[10:11]
	s_mov_b32 s10, 0x16816817
	s_mov_b32 s11, 0xbf768168
	v_cndmask_b32_e32 v7, 0, v7, vcc
	v_cmp_nlt_f32_e32 vcc, s8, v6
	s_mov_b32 s8, 0x11111111
	v_mul_f64 v[32:33], v[46:47], s[10:11]
	v_readlane_b32 s10, v246, 39
	s_mov_b32 s9, 0xbfa11111
	v_readlane_b32 s11, v246, 40
	v_mul_f64 v[16:17], v[46:47], s[8:9]
	s_mov_b32 s9, s11
	v_mul_f64 v[36:37], v[46:47], s[8:9]
	s_mov_b32 s8, 0x1ac5701b
	s_mov_b32 s6, 0x55555555
	s_mov_b32 s9, 0xbf6ac570
	s_mov_b32 s7, 0xbfb55555
	v_mul_f64 v[50:51], v[46:47], s[8:9]
	s_mov_b32 s8, 0x308158ed
	v_mul_f64 v[12:13], v[46:47], s[6:7]
	s_mov_b32 s7, s11
	s_mov_b32 s9, 0xbf658ed2
	v_writelane_b32 v246, s6, 39
	v_mul_f64 v[54:55], v[46:47], s[8:9]
	s_mov_b32 s8, 0x6b015ac0
	v_writelane_b32 v246, s7, 40
	s_mov_b32 s9, 0xbf55ac05
	v_mul_f64 v[56:57], v[46:47], s[8:9]
	v_readlane_b32 s8, v246, 41
	v_readlane_b32 s9, v246, 42
	s_mov_b32 s7, s9
	v_mul_f64 v[38:39], v[46:47], s[6:7]
	v_fma_f64 v[58:59], v[46:47], s[6:7], 1.0
	s_mov_b32 s6, 0x9999999a
	s_mov_b32 s7, 0xbfa99999
	v_mul_f64 v[40:41], v[46:47], s[6:7]
	s_mov_b32 s6, 0x18618618
	s_mov_b32 s7, 0xbf986186
	v_mul_f64 v[60:61], v[38:39], v[40:41]
	v_fmac_f64_e32 v[58:59], v[38:39], v[40:41]
	v_mul_f64 v[38:39], v[46:47], s[6:7]
	s_mov_b32 s6, 0x1c71c71c
	s_mov_b32 s7, 0xbf8c71c7
	v_mul_f64 v[40:41], v[38:39], v[60:61]
	v_fmac_f64_e32 v[58:59], v[38:39], v[60:61]
	v_mul_f64 v[38:39], v[46:47], s[6:7]
	s_mov_b32 s6, 0x29e4129e
	s_mov_b32 s7, 0xbf829e41
	v_mul_f64 v[60:61], v[38:39], v[40:41]
	v_fmac_f64_e32 v[58:59], v[38:39], v[40:41]
	v_mul_f64 v[38:39], v[46:47], s[6:7]
	s_mov_b32 s6, 0x1a41a41a
	v_mul_f64 v[10:11], v[46:47], -0.5
	s_mov_b32 s7, 0xbf7a41a4
	v_fma_f64 v[68:69], v[46:47], -0.5, 1.0
	v_mul_f64 v[14:15], v[10:11], v[12:13]
	v_writelane_b32 v246, s8, 41
	v_mul_f64 v[40:41], v[38:39], v[60:61]
	v_fmac_f64_e32 v[58:59], v[38:39], v[60:61]
	v_mul_f64 v[38:39], v[46:47], s[6:7]
	s_mov_b32 s6, 0x13813814
	v_fmac_f64_e32 v[68:69], v[10:11], v[12:13]
	v_mul_f64 v[18:19], v[16:17], v[14:15]
	v_writelane_b32 v246, s9, 42
	s_mov_b32 s7, 0xbf738138
	s_mov_b32 s8, 0x1e1e1e1e
	v_fmac_f64_e32 v[68:69], v[16:17], v[14:15]
	v_pk_mul_f32 v[10:11], v[8:9], v[8:9]
	v_mul_f64 v[22:23], v[20:21], v[18:19]
	v_mul_f64 v[60:61], v[38:39], v[40:41]
	v_fmac_f64_e32 v[58:59], v[38:39], v[40:41]
	v_mul_f64 v[38:39], v[46:47], s[6:7]
	s_mov_b32 s9, 0xbf6e1e1e
	v_fmac_f64_e32 v[68:69], v[20:21], v[18:19]
	v_add_f32_e32 v3, v10, v11
	v_mul_f64 v[26:27], v[24:25], v[22:23]
	v_mul_f64 v[40:41], v[38:39], v[60:61]
	v_fmac_f64_e32 v[58:59], v[38:39], v[60:61]
	v_mul_f64 v[38:39], v[46:47], s[8:9]
	s_mov_b32 s8, 0xfd017f40
	v_fmac_f64_e32 v[68:69], v[24:25], v[22:23]
	v_rcp_f32_e32 v70, v3
	v_lshlrev_b32_e32 v3, 6, v42
	v_mul_f64 v[30:31], v[28:29], v[26:27]
	s_mov_b32 s9, 0xbf67f405
; DI void s5_coef(const Params& P, int l, int g, int p, S5Coef& C) {
;     ...
;   double s, c; sincos_d((double)(li * dt), s, c);
;   C.ar = mag * (float)c; C.ai = mag * (float)s;
;   const float inv_den = __builtin_amdgcn_rcpf(lr * lr + li * li);
;   float fr = ((C.ar - 1.f) * lr + C.ai * li) * inv_den;
;   float fi = (C.ai * lr - (C.ar - 1.f) * li) * inv_den;
;   const float4* br4 = (const float4*)(P.in[14] + ((long)(l * 16 + g) * 64 + p) * 16);
;   const float4* bi4 = (const float4*)(P.in[15] + ((long)(l * 16 + g) * 64 + p) * 16);
; #pragma unroll
;   for (int q = 0; q < 4; ++q) {
;     const float4 r4 = br4[q], i4 = bi4[q];
;     C.bbr[4 * q + 0] = fr * r4.x - fi * i4.x; C.bbi[4 * q + 0] = fr * i4.x + fi * r4.x;
;     C.bbr[4 * q + 1] = fr * r4.y - fi * i4.y; C.bbi[4 * q + 1] = fr * i4.y + fi * r4.y;
;     C.bbr[4 * q + 2] = fr * r4.z - fi * i4.z; C.bbi[4 * q + 2] = fr * i4.z + fi * r4.z;
;     C.bbr[4 * q + 3] = fr * r4.w - fi * i4.w; C.bbi[4 * q + 3] = fr * i4.w + fi * r4.w;
;   }
	v_fmac_f64_e32 v[68:69], v[28:29], v[26:27]
	v_or_b32_e32 v4, v4, v3
	v_mul_f64 v[34:35], v[32:33], v[30:31]
	v_mul_f64 v[60:61], v[38:39], v[40:41]
	v_fmac_f64_e32 v[58:59], v[38:39], v[40:41]
	v_mul_f64 v[38:39], v[46:47], s[8:9]
	v_fmac_f64_e32 v[68:69], v[32:33], v[30:31]
	v_lshl_add_u64 v[10:11], s[84:85], 0, v[4:5]
	v_mul_f64 v[48:49], v[36:37], v[34:35]
	v_mul_f64 v[62:63], v[38:39], v[60:61]
	v_fmac_f64_e32 v[58:59], v[38:39], v[60:61]
	v_fmac_f64_e32 v[68:69], v[36:37], v[34:35]
	v_lshl_add_u64 v[4:5], s[86:87], 0, v[4:5]
	global_load_dwordx4 v[34:37], v[10:11], off offset:48
	global_load_dwordx4 v[26:29], v[10:11], off offset:32
	global_load_dwordx4 v[18:21], v[10:11], off offset:16
	s_nop 0
	global_load_dwordx4 v[10:13], v[10:11], off
	s_nop 0
	global_load_dwordx4 v[38:41], v[4:5], off offset:48
	global_load_dwordx4 v[30:33], v[4:5], off offset:32
	global_load_dwordx4 v[22:25], v[4:5], off offset:16
	global_load_dwordx4 v[14:17], v[4:5], off
	v_readlane_b32 s8, v246, 43
	v_readlane_b32 s9, v246, 44
	s_mov_b32 s7, s9
	v_mul_f64 v[60:61], v[46:47], s[6:7]
	s_mov_b32 s6, 0xb51f5e1a
	s_mov_b32 s7, 0xbf603091
	v_mul_f64 v[66:67], v[46:47], s[6:7]
	s_mov_b32 s6, 0xb4e81b4f
	s_mov_b32 s7, 0xbf5b4e81
	v_mul_f64 v[74:75], v[46:47], s[6:7]
	s_mov_b32 s6, 0x4046ed29
	s_mov_b32 s7, 0xbf61bb4a
	v_mul_f64 v[76:77], v[46:47], s[6:7]
	s_mov_b32 s6, 0x76b981db
	s_mov_b32 s7, 0xbf5dae60
	v_mul_f64 v[82:83], v[46:47], s[6:7]
	s_mov_b32 s6, 0xc201756d
	s_mov_b32 s7, 0xbf5756ca
	v_mul_f64 v[84:85], v[46:47], s[6:7]
	s_mov_b32 s6, 0x25d51f87
	v_mul_f64 v[52:53], v[50:51], v[48:49]
	v_mul_f64 v[64:65], v[60:61], v[62:63]
	s_mov_b32 s7, 0xbf542d66
	v_fmac_f64_e32 v[68:69], v[50:51], v[48:49]
	v_fmac_f64_e32 v[58:59], v[60:61], v[62:63]
	v_mul_f64 v[4:5], v[66:67], v[64:65]
	v_mul_f64 v[72:73], v[54:55], v[52:53]
	v_mul_f64 v[90:91], v[46:47], s[6:7]
	s_mov_b32 s6, 0x7f9b2ce6
	v_fmac_f64_e32 v[58:59], v[66:67], v[64:65]
	v_fmac_f64_e32 v[68:69], v[54:55], v[52:53]
	v_mul_f64 v[78:79], v[76:77], v[72:73]
	v_mul_f64 v[80:81], v[74:75], v[4:5]
	s_mov_b32 s7, 0xbf5934c6
	v_fmac_f64_e32 v[68:69], v[76:77], v[72:73]
	v_fmac_f64_e32 v[58:59], v[74:75], v[4:5]
	v_mul_f64 v[86:87], v[84:85], v[80:81]
	v_mul_f64 v[88:89], v[82:83], v[78:79]
	v_mul_f64 v[46:47], v[46:47], s[6:7]
	v_fmac_f64_e32 v[58:59], v[84:85], v[80:81]
	v_fmac_f64_e32 v[68:69], v[82:83], v[78:79]
	v_mul_f64 v[92:93], v[46:47], v[88:89]
	v_fmac_f64_e32 v[68:69], v[46:47], v[88:89]
	v_fmac_f64_e32 v[58:59], v[90:91], v[86:87]
	v_fmac_f64_e32 v[68:69], v[56:57], v[92:93]
	v_mul_f64 v[4:5], v[58:59], v[44:45]
	v_cndmask_b32_e32 v6, v187, v7, vcc
	v_cvt_f32_f64_e32 v44, v[68:69]
	v_cvt_f32_f64_e32 v45, v[4:5]
	v_pk_mul_f32 v[4:5], v[6:7], v[44:45] op_sel_hi:[0,1]
	v_add_f32_e32 v6, -1.0, v4
	v_mov_b32_e32 v7, v5
	v_mov_b32_e32 v44, v9
	v_pk_mul_f32 v[44:45], v[44:45], v[6:7] op_sel:[0,1] op_sel_hi:[0,0]
	v_pk_fma_f32 v[46:47], v[8:9], v[6:7], v[44:45]
	v_pk_fma_f32 v[6:7], v[8:9], v[6:7], v[44:45] op_sel_hi:[0,1,1] neg_lo:[0,0,1] neg_hi:[0,0,1]
	v_mov_b32_e32 v47, v7
	v_pk_mul_f32 v[44:45], v[70:71], v[46:47] op_sel_hi:[0,1]
	s_lshl_b32 s6, s5, 12
	s_lshl_b32 s7, s4, 6
	s_or_b32 s6, s7, s6
	v_or_b32_e32 v3, v1, v3
	v_writelane_b32 v246, s8, 43
	s_waitcnt vmcnt(0)
	v_pk_mul_f32 v[8:9], v[14:15], v[44:45] op_sel:[0,1] op_sel_hi:[0,0]
	v_pk_fma_f32 v[6:7], v[10:11], v[44:45], v[8:9] neg_lo:[0,0,1] neg_hi:[0,0,1]
	v_pk_fma_f32 v[8:9], v[10:11], v[44:45], v[8:9] op_sel_hi:[0,1,1]
	v_pk_mul_f32 v[14:15], v[14:15], v[44:45] op_sel:[1,1] op_sel_hi:[1,0]
	v_mov_b32_e32 v8, v11
	v_mov_b32_e32 v7, v9
	v_pk_fma_f32 v[8:9], v[8:9], v[44:45], v[14:15] neg_lo:[0,0,1] neg_hi:[0,0,1]
	v_pk_fma_f32 v[10:11], v[10:11], v[44:45], v[14:15] op_sel:[1,0,0]
	v_pk_mul_f32 v[14:15], v[16:17], v[44:45] op_sel:[0,1] op_sel_hi:[0,0]
	v_mov_b32_e32 v9, v11
	v_pk_fma_f32 v[10:11], v[12:13], v[44:45], v[14:15] neg_lo:[0,0,1] neg_hi:[0,0,1]
	v_pk_fma_f32 v[14:15], v[12:13], v[44:45], v[14:15] op_sel_hi:[0,1,1]
	v_mov_b32_e32 v12, v17
	v_mov_b32_e32 v11, v15
	v_pk_mul_f32 v[14:15], v[12:13], v[44:45] op_sel:[0,1] op_sel_hi:[0,0]
	v_mov_b32_e32 v12, v13
	v_mov_b32_e32 v16, v13
	v_pk_fma_f32 v[12:13], v[12:13], v[44:45], v[14:15] neg_lo:[0,0,1] neg_hi:[0,0,1]
	v_pk_fma_f32 v[14:15], v[16:17], v[44:45], v[14:15] op_sel_hi:[0,1,1]
	v_pk_mul_f32 v[16:17], v[22:23], v[44:45] op_sel:[0,1] op_sel_hi:[0,0]
	v_mov_b32_e32 v13, v15
	v_pk_fma_f32 v[14:15], v[18:19], v[44:45], v[16:17] neg_lo:[0,0,1] neg_hi:[0,0,1]
	v_pk_fma_f32 v[16:17], v[18:19], v[44:45], v[16:17] op_sel_hi:[0,1,1]
	v_pk_mul_f32 v[22:23], v[22:23], v[44:45] op_sel:[1,1] op_sel_hi:[1,0]
	v_mov_b32_e32 v16, v19
	v_mov_b32_e32 v15, v17
	v_pk_fma_f32 v[16:17], v[16:17], v[44:45], v[22:23] neg_lo:[0,0,1] neg_hi:[0,0,1]
	v_pk_fma_f32 v[18:19], v[18:19], v[44:45], v[22:23] op_sel:[1,0,0]
	v_pk_mul_f32 v[22:23], v[24:25], v[44:45] op_sel:[0,1] op_sel_hi:[0,0]
	v_mov_b32_e32 v17, v19
	v_pk_fma_f32 v[18:19], v[20:21], v[44:45], v[22:23] neg_lo:[0,0,1] neg_hi:[0,0,1]
	v_pk_fma_f32 v[22:23], v[20:21], v[44:45], v[22:23] op_sel_hi:[0,1,1]
	v_mov_b32_e32 v20, v25
	v_mov_b32_e32 v19, v23
	v_pk_mul_f32 v[22:23], v[20:21], v[44:45] op_sel:[0,1] op_sel_hi:[0,0]
	v_mov_b32_e32 v20, v21
	v_mov_b32_e32 v24, v21
	v_pk_fma_f32 v[20:21], v[20:21], v[44:45], v[22:23] neg_lo:[0,0,1] neg_hi:[0,0,1]
	v_pk_fma_f32 v[22:23], v[24:25], v[44:45], v[22:23] op_sel_hi:[0,1,1]
	v_pk_mul_f32 v[24:25], v[30:31], v[44:45] op_sel:[0,1] op_sel_hi:[0,0]
	v_mov_b32_e32 v21, v23
	v_pk_fma_f32 v[22:23], v[26:27], v[44:45], v[24:25] neg_lo:[0,0,1] neg_hi:[0,0,1]
	v_pk_fma_f32 v[24:25], v[26:27], v[44:45], v[24:25] op_sel_hi:[0,1,1]
; DI int TID() { int t = threadIdx.x; asm volatile("" : "+v"(t)); return t; }
; DI unsigned char* WSP(const Params& P) { size_t z = 0; asm volatile("" : "+s"(z)); return P.ws + z; }
; DI float bf2f(u16 h) { return __uint_as_float(((unsigned)h) << 16); }
; DI void s5_load_u(float* su, const u16* PROJ, int b, int chunk, int g, int lane) {
;   const u16* src = PROJ + ((long)(b * SEQ + chunk * 64 + lane)) * PW + P_S5U + g * 16;
;   uint4 v0 = ((const uint4*)src)[0], v1 = ((const uint4*)src)[1];
;   const unsigned* a = (const unsigned*)&v0; const unsigned* c = (const unsigned*)&v1;
;   float* d = su + lane * 16;
; #pragma unroll
;   for (int q = 0; q < 4; ++q) { d[2 * q] = bf2f((u16)(a[q] & 0xffff)); d[2 * q + 1] = bf2f((u16)(a[q] >> 16)); }
; #pragma unroll
;   for (int q = 0; q < 4; ++q) { d[8 + 2 * q] = bf2f((u16)(c[q] & 0xffff)); d[8 + 2 * q + 1] = bf2f((u16)(c[q] >> 16)); }
; }
; DI void s5_pass1_item(const Params& P, int l, int it, float* lds) {
;   const int lane = TID() & 63, w = TID() >> 6;
;   const int gq = it & 3, chunk = (it >> 2) & 63, b = it >> 8;
;   const int g = gq * 4 + w;
;   const u16* PROJ = (const u16*)(WSP(P) + WS_PROJ);
;   float* su = lds + w * 1024;
;   S5Coef C; s5_coef(P, l, g, lane, C);
;   s5_load_u(su, PROJ, b, chunk, g, lane);
;   __syncthreads();
;   float xr = 0.f, xi = 0.f;
; #pragma unroll 4
;   for (int t = 0; t < 64; ++t) {
;     const f32x4* up = (const f32x4*)(su + t * 16);
	v_pk_mul_f32 v[30:31], v[30:31], v[44:45] op_sel:[1,1] op_sel_hi:[1,0]
	v_mov_b32_e32 v24, v27
	v_mov_b32_e32 v23, v25
	v_pk_fma_f32 v[24:25], v[24:25], v[44:45], v[30:31] neg_lo:[0,0,1] neg_hi:[0,0,1]
	v_pk_fma_f32 v[26:27], v[26:27], v[44:45], v[30:31] op_sel:[1,0,0]
	v_pk_mul_f32 v[30:31], v[32:33], v[44:45] op_sel:[0,1] op_sel_hi:[0,0]
	v_mov_b32_e32 v25, v27
	v_pk_fma_f32 v[26:27], v[28:29], v[44:45], v[30:31] neg_lo:[0,0,1] neg_hi:[0,0,1]
	v_pk_fma_f32 v[30:31], v[28:29], v[44:45], v[30:31] op_sel_hi:[0,1,1]
	v_mov_b32_e32 v28, v33
	v_mov_b32_e32 v27, v31
	v_pk_mul_f32 v[30:31], v[28:29], v[44:45] op_sel:[0,1] op_sel_hi:[0,0]
	v_mov_b32_e32 v28, v29
	v_mov_b32_e32 v32, v29
	v_pk_fma_f32 v[28:29], v[28:29], v[44:45], v[30:31] neg_lo:[0,0,1] neg_hi:[0,0,1]
	v_pk_fma_f32 v[30:31], v[32:33], v[44:45], v[30:31] op_sel_hi:[0,1,1]
	v_pk_mul_f32 v[32:33], v[44:45], v[38:39] op_sel:[1,0] op_sel_hi:[0,0]
	v_mov_b32_e32 v29, v31
	v_pk_fma_f32 v[30:31], v[34:35], v[44:45], v[32:33] neg_lo:[0,0,1] neg_hi:[0,0,1]
	v_pk_fma_f32 v[32:33], v[34:35], v[44:45], v[32:33] op_sel_hi:[0,1,1]
	v_pk_mul_f32 v[38:39], v[44:45], v[38:39] op_sel:[1,1] op_sel_hi:[0,1]
	v_mov_b32_e32 v32, v35
	v_mov_b32_e32 v31, v33
	v_pk_fma_f32 v[32:33], v[32:33], v[44:45], v[38:39] neg_lo:[0,0,1] neg_hi:[0,0,1]
	v_pk_fma_f32 v[34:35], v[34:35], v[44:45], v[38:39] op_sel:[1,0,0]
	v_pk_mul_f32 v[38:39], v[44:45], v[40:41] op_sel:[1,0] op_sel_hi:[0,0]
	v_mov_b32_e32 v33, v35
	v_pk_fma_f32 v[34:35], v[36:37], v[44:45], v[38:39] neg_lo:[0,0,1] neg_hi:[0,0,1]
	v_pk_fma_f32 v[38:39], v[36:37], v[44:45], v[38:39] op_sel_hi:[0,1,1]
	v_mov_b32_e32 v36, v41
	v_mov_b32_e32 v35, v39
	v_pk_mul_f32 v[38:39], v[44:45], v[36:37] op_sel:[1,0] op_sel_hi:[0,0]
	v_mov_b32_e32 v36, v37
	v_mov_b32_e32 v40, v37
	v_pk_fma_f32 v[36:37], v[44:45], v[36:37], v[38:39] neg_lo:[0,0,1] neg_hi:[0,0,1]
	v_pk_fma_f32 v[38:39], v[44:45], v[40:41], v[38:39] op_sel_hi:[1,0,1]
	v_lshlrev_b32_e32 v40, 4, v0
	v_or_b32_e32 v38, s6, v42
	s_movk_i32 s6, 0xb00
	v_mul_lo_u32 v162, v38, s6
	v_mov_b32_e32 v37, v39
	v_lshl_add_u64 v[38:39], v[162:163], 1, s[0:1]
	v_ashrrev_i32_e32 v41, 31, v40
	v_lshl_add_u64 v[40:41], v[40:41], 1, v[38:39]
	s_mov_b64 s[0:1], 0x4000500
	v_lshl_add_u64 v[38:39], v[40:41], 0, s[0:1]
	s_brev_b32 s0, 32
	v_add_co_u32_e32 v40, vcc, s0, v40
	v_writelane_b32 v246, s9, 44
	s_nop 0
	v_addc_co_u32_e32 v41, vcc, 0, v41, vcc
	global_load_dwordx4 v[44:47], v[40:41], off offset:1280
	s_nop 0
	global_load_dwordx4 v[38:41], v[38:39], off offset:16
	s_mov_b32 s0, 0
	s_waitcnt vmcnt(1)
	v_lshlrev_b32_e32 v50, 16, v45
	v_lshlrev_b32_e32 v48, 16, v44
	v_lshlrev_b32_e32 v54, 16, v47
	v_lshlrev_b32_e32 v52, 16, v46
	v_and_b32_e32 v51, 0xffff0000, v45
	v_and_b32_e32 v49, 0xffff0000, v44
	v_and_b32_e32 v55, 0xffff0000, v47
	v_and_b32_e32 v53, 0xffff0000, v46
	ds_write_b128 v3, v[52:55] offset:16
	ds_write_b128 v3, v[48:51]
	s_waitcnt vmcnt(0)
	v_lshlrev_b32_e32 v50, 16, v41
	v_lshlrev_b32_e32 v48, 16, v40
	v_and_b32_e32 v51, 0xffff0000, v41
	v_and_b32_e32 v49, 0xffff0000, v40
	v_lshlrev_b32_e32 v46, 16, v39
	v_lshlrev_b32_e32 v44, 16, v38
	v_and_b32_e32 v47, 0xffff0000, v39
	v_and_b32_e32 v45, 0xffff0000, v38
	ds_write_b128 v3, v[48:51] offset:48
	ds_write_b128 v3, v[44:47] offset:32
	s_waitcnt lgkmcnt(0)
	s_barrier
	v_pk_mov_b32 v[38:39], v[4:5], v[4:5] op_sel:[1,0]
	v_mov_b32_e32 v40, 0
	v_mov_b32_e32 v3, v40
	v_add_u32_e32 v43, s0, v1
	ds_read_b128 v[44:47], v43
	ds_read_b128 v[48:51], v43 offset:16
	ds_read_b128 v[52:55], v43 offset:32
	ds_read_b128 v[56:59], v43 offset:48
	ds_read_b128 v[62:65], v43 offset:64
	ds_read_b128 v[66:69], v43 offset:80
	ds_read_b128 v[70:73], v43 offset:96
	ds_read_b128 v[74:77], v43 offset:112
; DI unsigned char* WSP(const Params& P) { size_t z = 0; asm volatile("" : "+s"(z)); return P.ws + z; }
; DI void s5_pass1_item(const Params& P, int l, int it, float* lds) {
;     ...
;   float xr = 0.f, xi = 0.f;
; #pragma unroll 4
;   for (int t = 0; t < 64; ++t) {
;     const f32x4* up = (const f32x4*)(su + t * 16);
;     float br = 0.f, bi = 0.f;
; #pragma unroll
;     for (int q = 0; q < 4; ++q) {
;       f32x4 u = up[q];
; #pragma unroll
;       for (int e = 0; e < 4; ++e) { br += u[e] * C.bbr[4 * q + e]; bi += u[e] * C.bbi[4 * q + e]; }
;     }
;     float nr = C.ar * xr - C.ai * xi + br;
;     float ni = C.ar * xi + C.ai * xr + bi;
;     xr = nr; xi = ni;
;   }
;   float2* ENDS = (float2*)(WSP(P) + WS_ENDS);
;   ENDS[((long)(b * 64 + chunk) * 16 + g) * 64 + lane] = make_float2(xr, xi);
.LBB0_516:
	s_waitcnt lgkmcnt(0)
	ds_read_b128 v[80:83], v43 offset:128
	ds_read_b128 v[84:87], v43 offset:144
	ds_read_b128 v[88:91], v43 offset:160
	ds_read_b128 v[92:95], v43 offset:176
	ds_read_b128 v[96:99], v43 offset:192
	ds_read_b128 v[100:103], v43 offset:208
	ds_read_b128 v[104:107], v43 offset:224
	ds_read_b128 v[108:111], v43 offset:240
	v_pk_fma_f32 v[60:61], v[6:7], v[44:45], 0 op_sel_hi:[1,0,0]
	v_pk_fma_f32 v[78:79], v[6:7], v[62:63], 0 op_sel_hi:[1,0,0]
	v_pk_fma_f32 v[60:61], v[8:9], v[44:45], v[60:61] op_sel:[0,1,0]
	v_pk_fma_f32 v[78:79], v[8:9], v[62:63], v[78:79] op_sel:[0,1,0]
	v_pk_fma_f32 v[60:61], v[10:11], v[46:47], v[60:61] op_sel_hi:[1,0,1]
	v_pk_fma_f32 v[78:79], v[10:11], v[64:65], v[78:79] op_sel_hi:[1,0,1]
	v_pk_fma_f32 v[60:61], v[12:13], v[46:47], v[60:61] op_sel:[0,1,0]
	v_pk_fma_f32 v[78:79], v[12:13], v[64:65], v[78:79] op_sel:[0,1,0]
	v_pk_fma_f32 v[60:61], v[14:15], v[48:49], v[60:61] op_sel_hi:[1,0,1]
	v_pk_fma_f32 v[78:79], v[14:15], v[66:67], v[78:79] op_sel_hi:[1,0,1]
	v_pk_fma_f32 v[60:61], v[16:17], v[48:49], v[60:61] op_sel:[0,1,0]
	v_pk_fma_f32 v[78:79], v[16:17], v[66:67], v[78:79] op_sel:[0,1,0]
	v_pk_fma_f32 v[60:61], v[18:19], v[50:51], v[60:61] op_sel_hi:[1,0,1]
	v_pk_fma_f32 v[78:79], v[18:19], v[68:69], v[78:79] op_sel_hi:[1,0,1]
	v_pk_fma_f32 v[60:61], v[20:21], v[50:51], v[60:61] op_sel:[0,1,0]
	v_pk_fma_f32 v[78:79], v[20:21], v[68:69], v[78:79] op_sel:[0,1,0]
	v_pk_fma_f32 v[60:61], v[22:23], v[52:53], v[60:61] op_sel_hi:[1,0,1]
	v_pk_fma_f32 v[78:79], v[22:23], v[70:71], v[78:79] op_sel_hi:[1,0,1]
	v_pk_fma_f32 v[60:61], v[24:25], v[52:53], v[60:61] op_sel:[0,1,0]
	v_pk_fma_f32 v[78:79], v[24:25], v[70:71], v[78:79] op_sel:[0,1,0]
	v_pk_fma_f32 v[60:61], v[26:27], v[54:55], v[60:61] op_sel_hi:[1,0,1]
	v_pk_fma_f32 v[78:79], v[26:27], v[72:73], v[78:79] op_sel_hi:[1,0,1]
	v_pk_fma_f32 v[60:61], v[28:29], v[54:55], v[60:61] op_sel:[0,1,0]
	v_pk_fma_f32 v[78:79], v[28:29], v[72:73], v[78:79] op_sel:[0,1,0]
	v_pk_fma_f32 v[60:61], v[30:31], v[56:57], v[60:61] op_sel_hi:[1,0,1]
	v_pk_fma_f32 v[78:79], v[30:31], v[74:75], v[78:79] op_sel_hi:[1,0,1]
	v_pk_fma_f32 v[60:61], v[32:33], v[56:57], v[60:61] op_sel:[0,1,0]
	v_pk_fma_f32 v[78:79], v[32:33], v[74:75], v[78:79] op_sel:[0,1,0]
	v_pk_fma_f32 v[60:61], v[34:35], v[58:59], v[60:61] op_sel_hi:[1,0,1]
	v_pk_fma_f32 v[78:79], v[34:35], v[76:77], v[78:79] op_sel_hi:[1,0,1]
	v_pk_fma_f32 v[60:61], v[36:37], v[58:59], v[60:61] op_sel:[0,1,0]
	v_pk_fma_f32 v[78:79], v[36:37], v[76:77], v[78:79] op_sel:[0,1,0]
	v_pk_mul_f32 v[40:41], v[38:39], v[2:3] op_sel:[0,1]
	s_nop 0
	v_pk_fma_f32 v[112:113], v[4:5], v[2:3], v[40:41] neg_lo:[0,0,1] neg_hi:[0,0,1]
	v_pk_fma_f32 v[2:3], v[4:5], v[2:3], v[40:41] op_sel_hi:[1,0,1]
	s_nop 0
	v_mov_b32_e32 v113, v3
	s_nop 0
	v_pk_add_f32 v[2:3], v[112:113], v[60:61]
	s_nop 0
	v_pk_mul_f32 v[40:41], v[38:39], v[2:3] op_sel:[0,1]
	s_nop 0
	v_pk_fma_f32 v[112:113], v[4:5], v[2:3], v[40:41] neg_lo:[0,0,1] neg_hi:[0,0,1]
	v_pk_fma_f32 v[2:3], v[4:5], v[2:3], v[40:41] op_sel_hi:[1,0,1]
	s_nop 0
	v_mov_b32_e32 v113, v3
	s_nop 0
	v_pk_add_f32 v[2:3], v[112:113], v[78:79]
	s_nop 0
	s_addk_i32 s0, 0x100
	v_add_u32_e32 v43, s0, v1
	s_waitcnt lgkmcnt(0)
	ds_read_b128 v[44:47], v43
	ds_read_b128 v[48:51], v43 offset:16
	ds_read_b128 v[52:55], v43 offset:32
	ds_read_b128 v[56:59], v43 offset:48
	ds_read_b128 v[62:65], v43 offset:64
	ds_read_b128 v[66:69], v43 offset:80
	ds_read_b128 v[70:73], v43 offset:96
	ds_read_b128 v[74:77], v43 offset:112
	v_pk_fma_f32 v[60:61], v[6:7], v[80:81], 0 op_sel_hi:[1,0,0]
	v_pk_fma_f32 v[78:79], v[6:7], v[96:97], 0 op_sel_hi:[1,0,0]
	v_pk_fma_f32 v[60:61], v[8:9], v[80:81], v[60:61] op_sel:[0,1,0]
	v_pk_fma_f32 v[78:79], v[8:9], v[96:97], v[78:79] op_sel:[0,1,0]
	v_pk_fma_f32 v[60:61], v[10:11], v[82:83], v[60:61] op_sel_hi:[1,0,1]
	v_pk_fma_f32 v[78:79], v[10:11], v[98:99], v[78:79] op_sel_hi:[1,0,1]
	v_pk_fma_f32 v[60:61], v[12:13], v[82:83], v[60:61] op_sel:[0,1,0]
	v_pk_fma_f32 v[78:79], v[12:13], v[98:99], v[78:79] op_sel:[0,1,0]
	v_pk_fma_f32 v[60:61], v[14:15], v[84:85], v[60:61] op_sel_hi:[1,0,1]
	v_pk_fma_f32 v[78:79], v[14:15], v[100:101], v[78:79] op_sel_hi:[1,0,1]
	v_pk_fma_f32 v[60:61], v[16:17], v[84:85], v[60:61] op_sel:[0,1,0]
	v_pk_fma_f32 v[78:79], v[16:17], v[100:101], v[78:79] op_sel:[0,1,0]
	v_pk_fma_f32 v[60:61], v[18:19], v[86:87], v[60:61] op_sel_hi:[1,0,1]
	v_pk_fma_f32 v[78:79], v[18:19], v[102:103], v[78:79] op_sel_hi:[1,0,1]
	v_pk_fma_f32 v[60:61], v[20:21], v[86:87], v[60:61] op_sel:[0,1,0]
	v_pk_fma_f32 v[78:79], v[20:21], v[102:103], v[78:79] op_sel:[0,1,0]
	v_pk_fma_f32 v[60:61], v[22:23], v[88:89], v[60:61] op_sel_hi:[1,0,1]
	v_pk_fma_f32 v[78:79], v[22:23], v[104:105], v[78:79] op_sel_hi:[1,0,1]
	v_pk_fma_f32 v[60:61], v[24:25], v[88:89], v[60:61] op_sel:[0,1,0]
	v_pk_fma_f32 v[78:79], v[24:25], v[104:105], v[78:79] op_sel:[0,1,0]
	v_pk_fma_f32 v[60:61], v[26:27], v[90:91], v[60:61] op_sel_hi:[1,0,1]
	v_pk_fma_f32 v[78:79], v[26:27], v[106:107], v[78:79] op_sel_hi:[1,0,1]
	v_pk_fma_f32 v[60:61], v[28:29], v[90:91], v[60:61] op_sel:[0,1,0]
	v_pk_fma_f32 v[78:79], v[28:29], v[106:107], v[78:79] op_sel:[0,1,0]
	v_pk_fma_f32 v[60:61], v[30:31], v[92:93], v[60:61] op_sel_hi:[1,0,1]
	v_pk_fma_f32 v[78:79], v[30:31], v[108:109], v[78:79] op_sel_hi:[1,0,1]
	v_pk_fma_f32 v[60:61], v[32:33], v[92:93], v[60:61] op_sel:[0,1,0]
	v_pk_fma_f32 v[78:79], v[32:33], v[108:109], v[78:79] op_sel:[0,1,0]
	v_pk_fma_f32 v[60:61], v[34:35], v[94:95], v[60:61] op_sel_hi:[1,0,1]
	v_pk_fma_f32 v[78:79], v[34:35], v[110:111], v[78:79] op_sel_hi:[1,0,1]
	v_pk_fma_f32 v[60:61], v[36:37], v[94:95], v[60:61] op_sel:[0,1,0]
	v_pk_fma_f32 v[78:79], v[36:37], v[110:111], v[78:79] op_sel:[0,1,0]
	v_pk_mul_f32 v[40:41], v[38:39], v[2:3] op_sel:[0,1]
	s_nop 0
	v_pk_fma_f32 v[112:113], v[4:5], v[2:3], v[40:41] neg_lo:[0,0,1] neg_hi:[0,0,1]
	v_pk_fma_f32 v[2:3], v[4:5], v[2:3], v[40:41] op_sel_hi:[1,0,1]
	s_nop 0
	v_mov_b32_e32 v113, v3
	s_nop 0
	v_pk_add_f32 v[2:3], v[112:113], v[60:61]
	s_nop 0
	v_pk_mul_f32 v[40:41], v[38:39], v[2:3] op_sel:[0,1]
	s_nop 0
	v_pk_fma_f32 v[112:113], v[4:5], v[2:3], v[40:41] neg_lo:[0,0,1] neg_hi:[0,0,1]
	v_pk_fma_f32 v[2:3], v[4:5], v[2:3], v[40:41] op_sel_hi:[1,0,1]
	s_nop 0
	v_mov_b32_e32 v113, v3
	s_nop 0
	v_pk_add_f32 v[2:3], v[112:113], v[78:79]
	s_nop 0
	s_cmpk_lg_i32 s0, 0x1000
	s_cbranch_scc1 .LBB0_516
	s_waitcnt lgkmcnt(0)
	s_mov_b64 s[0:1], 0
	s_add_u32 s0, s70, s0
	s_addc_u32 s1, s71, s1
	s_lshl_b32 s5, s5, 10
	s_lshl_b32 s4, s4, 4
	s_or_b32 s46, s4, s5
	v_ashrrev_i32_e32 v1, 31, v0
	v_lshl_add_u64 v[0:1], v[0:1], 0, s[46:47]
	v_lshlrev_b64 v[0:1], 9, v[0:1]
	v_lshl_add_u64 v[0:1], s[0:1], 0, v[0:1]
	v_lshlrev_b32_e32 v162, 3, v42
	v_lshl_add_u64 v[0:1], v[0:1], 0, v[162:163]
	v_add_co_u32_e32 v0, vcc, 0x1c400000, v0
	s_nop 1
	v_addc_co_u32_e32 v1, vcc, 0, v1, vcc
	global_store_dwordx2 v[0:1], v[2:3], off

; DI void phase_convert(const Params& P, int l, float* lds) {
;     ...
;     {
;       const int n = tid & 63;
;       long ld; const float* cp = conv_colptr(P, l, mat, nb * 64 + n, ld);
; #pragma unroll 4
;       for (int q = 0; q < 16; ++q) { int k = (tid >> 6) + 4 * q; lds[n * 65 + k] = cp[(long)(kb * 64 + k) * ld]; }
;     }
.LBB0_753:
	s_mul_i32 s23, s23, s19
	s_sub_i32 s16, s22, s23
	s_lshl_b32 s16, s16, 6
	s_mov_b32 s17, s14
	s_mov_b32 s21, s15
	s_mov_b32 s22, s16
	s_mov_b32 s23, 1
	s_mov_b32 s24, 0
	s_mov_b32 s25, 16
	s_movk_i32 s26, 4
	s_movk_i32 s27, 0
	v_add_u32_e32 v26, s26, v1
	v_add_u32_e32 v23, s27, v2
	v_add_u32_e32 v16, s22, v26
	v_add_u32_e32 v24, s16, v23
	v_ashrrev_i32_e32 v17, 31, v16
	v_ashrrev_i32_e32 v25, 31, v24
	v_mul_lo_u32 v27, s17, v17
	v_mul_lo_u32 v28, s21, v16
	v_mad_u64_u32 v[16:17], s[28:29], s17, v16, 0
	v_add3_u32 v17, v17, v27, v28
	v_mul_lo_u32 v27, s14, v25
	v_mul_lo_u32 v28, s15, v24
	v_mad_u64_u32 v[24:25], s[28:29], s14, v24, 0
	v_add3_u32 v25, v25, v27, v28
	v_lshl_add_u64 v[24:25], v[24:25], 2, v[14:15]
	v_lshl_add_u64 v[16:17], v[16:17], 2, v[14:15]
	global_load_dword v30, v[24:25], off
	global_load_dword v31, v[16:17], off
	v_lshl_add_u32 v46, v23, 2, v18
	v_lshl_add_u32 v47, v26, 2, v18
	v_add_u32_e32 v26, s26, v3
	v_add_u32_e32 v23, s27, v8
	v_add_u32_e32 v16, s22, v26
	v_add_u32_e32 v24, s16, v23
	v_ashrrev_i32_e32 v17, 31, v16
	v_ashrrev_i32_e32 v25, 31, v24
	v_mul_lo_u32 v27, s17, v17
	v_mul_lo_u32 v28, s21, v16
	v_mad_u64_u32 v[16:17], s[28:29], s17, v16, 0
	v_add3_u32 v17, v17, v27, v28
	v_mul_lo_u32 v27, s14, v25
	v_mul_lo_u32 v28, s15, v24
	v_mad_u64_u32 v[24:25], s[28:29], s14, v24, 0
	v_add3_u32 v25, v25, v27, v28
	v_lshl_add_u64 v[24:25], v[24:25], 2, v[14:15]
	v_lshl_add_u64 v[16:17], v[16:17], 2, v[14:15]
	global_load_dword v32, v[24:25], off
	global_load_dword v33, v[16:17], off
	v_lshl_add_u32 v48, v23, 2, v18
	v_lshl_add_u32 v49, v26, 2, v18
	v_add_u32_e32 v26, s26, v9
	v_add_u32_e32 v23, s27, v10
	v_add_u32_e32 v16, s22, v26
	v_add_u32_e32 v24, s16, v23
	v_ashrrev_i32_e32 v17, 31, v16
	v_ashrrev_i32_e32 v25, 31, v24
	v_mul_lo_u32 v27, s17, v17
	v_mul_lo_u32 v28, s21, v16
	v_mad_u64_u32 v[16:17], s[28:29], s17, v16, 0
	v_add3_u32 v17, v17, v27, v28
	v_mul_lo_u32 v27, s14, v25
	v_mul_lo_u32 v28, s15, v24
	v_mad_u64_u32 v[24:25], s[28:29], s14, v24, 0
	v_add3_u32 v25, v25, v27, v28
	v_lshl_add_u64 v[24:25], v[24:25], 2, v[14:15]
	v_lshl_add_u64 v[16:17], v[16:17], 2, v[14:15]
	global_load_dword v34, v[24:25], off
	global_load_dword v35, v[16:17], off
	v_lshl_add_u32 v50, v23, 2, v18
	v_lshl_add_u32 v51, v26, 2, v18
	v_add_u32_e32 v26, s26, v11
	v_add_u32_e32 v23, s27, v12
	v_add_u32_e32 v16, s22, v26
	v_add_u32_e32 v24, s16, v23
	v_ashrrev_i32_e32 v17, 31, v16
	v_ashrrev_i32_e32 v25, 31, v24
	v_mul_lo_u32 v27, s17, v17
	v_mul_lo_u32 v28, s21, v16
	v_mad_u64_u32 v[16:17], s[28:29], s17, v16, 0
	v_add3_u32 v17, v17, v27, v28
	v_mul_lo_u32 v27, s14, v25
	v_mul_lo_u32 v28, s15, v24
	v_mad_u64_u32 v[24:25], s[28:29], s14, v24, 0
	v_add3_u32 v25, v25, v27, v28
	v_lshl_add_u64 v[24:25], v[24:25], 2, v[14:15]
	v_lshl_add_u64 v[16:17], v[16:17], 2, v[14:15]
	global_load_dword v36, v[24:25], off
	global_load_dword v37, v[16:17], off
	v_lshl_add_u32 v52, v23, 2, v18
	v_lshl_add_u32 v53, v26, 2, v18
	s_movk_i32 s26, 36
	s_movk_i32 s27, 32
	v_add_u32_e32 v26, s26, v1
	v_add_u32_e32 v23, s27, v2
	v_add_u32_e32 v16, s22, v26
	v_add_u32_e32 v24, s16, v23
	v_ashrrev_i32_e32 v17, 31, v16
	v_ashrrev_i32_e32 v25, 31, v24
	v_mul_lo_u32 v27, s17, v17
	v_mul_lo_u32 v28, s21, v16
	v_mad_u64_u32 v[16:17], s[28:29], s17, v16, 0
	v_add3_u32 v17, v17, v27, v28
	v_mul_lo_u32 v27, s14, v25
	v_mul_lo_u32 v28, s15, v24
	v_mad_u64_u32 v[24:25], s[28:29], s14, v24, 0
	v_add3_u32 v25, v25, v27, v28
	v_lshl_add_u64 v[24:25], v[24:25], 2, v[14:15]
	v_lshl_add_u64 v[16:17], v[16:17], 2, v[14:15]
	global_load_dword v38, v[24:25], off
	global_load_dword v39, v[16:17], off
	v_lshl_add_u32 v54, v23, 2, v18
	v_lshl_add_u32 v55, v26, 2, v18
	v_add_u32_e32 v26, s26, v3
	v_add_u32_e32 v23, s27, v8
	v_add_u32_e32 v16, s22, v26
	v_add_u32_e32 v24, s16, v23
	v_ashrrev_i32_e32 v17, 31, v16
	v_ashrrev_i32_e32 v25, 31, v24
	v_mul_lo_u32 v27, s17, v17
	v_mul_lo_u32 v28, s21, v16
	v_mad_u64_u32 v[16:17], s[28:29], s17, v16, 0
	v_add3_u32 v17, v17, v27, v28
	v_mul_lo_u32 v27, s14, v25
	v_mul_lo_u32 v28, s15, v24
	v_mad_u64_u32 v[24:25], s[28:29], s14, v24, 0
	v_add3_u32 v25, v25, v27, v28
	v_lshl_add_u64 v[24:25], v[24:25], 2, v[14:15]
	v_lshl_add_u64 v[16:17], v[16:17], 2, v[14:15]
	global_load_dword v40, v[24:25], off
	global_load_dword v41, v[16:17], off
	v_lshl_add_u32 v56, v23, 2, v18
	v_lshl_add_u32 v57, v26, 2, v18
	v_add_u32_e32 v26, s26, v9
	v_add_u32_e32 v23, s27, v10
	v_add_u32_e32 v16, s22, v26
	v_add_u32_e32 v24, s16, v23
	v_ashrrev_i32_e32 v17, 31, v16
	v_ashrrev_i32_e32 v25, 31, v24
	v_mul_lo_u32 v27, s17, v17
	v_mul_lo_u32 v28, s21, v16
	v_mad_u64_u32 v[16:17], s[28:29], s17, v16, 0
	v_add3_u32 v17, v17, v27, v28
	v_mul_lo_u32 v27, s14, v25
	v_mul_lo_u32 v28, s15, v24
	v_mad_u64_u32 v[24:25], s[28:29], s14, v24, 0
	v_add3_u32 v25, v25, v27, v28
	v_lshl_add_u64 v[24:25], v[24:25], 2, v[14:15]
	v_lshl_add_u64 v[16:17], v[16:17], 2, v[14:15]
	global_load_dword v42, v[24:25], off
	global_load_dword v43, v[16:17], off
	v_lshl_add_u32 v58, v23, 2, v18
	v_lshl_add_u32 v59, v26, 2, v18
	v_add_u32_e32 v26, s26, v11
	v_add_u32_e32 v23, s27, v12
	v_add_u32_e32 v16, s22, v26
	v_add_u32_e32 v24, s16, v23
	v_ashrrev_i32_e32 v17, 31, v16
	v_ashrrev_i32_e32 v25, 31, v24
	v_mul_lo_u32 v27, s17, v17
	v_mul_lo_u32 v28, s21, v16
	v_mad_u64_u32 v[16:17], s[28:29], s17, v16, 0
	v_add3_u32 v17, v17, v27, v28
	v_mul_lo_u32 v27, s14, v25
	v_mul_lo_u32 v28, s15, v24
	v_mad_u64_u32 v[24:25], s[28:29], s14, v24, 0
	v_add3_u32 v25, v25, v27, v28
	v_lshl_add_u64 v[24:25], v[24:25], 2, v[14:15]
	v_lshl_add_u64 v[16:17], v[16:17], 2, v[14:15]
	global_load_dword v44, v[24:25], off
	global_load_dword v45, v[16:17], off
	v_lshl_add_u32 v60, v23, 2, v18
	v_lshl_add_u32 v61, v26, 2, v18
	s_mov_b32 s23, 17
	s_mov_b32 s24, 16
	s_mov_b32 s25, 0
	s_waitcnt vmcnt(0)
	ds_write_b32 v46, v30
	ds_write_b32 v47, v31
	ds_write_b32 v48, v32
	ds_write_b32 v49, v33
	ds_write_b32 v50, v34
	ds_write_b32 v51, v35
	ds_write_b32 v52, v36
	ds_write_b32 v53, v37
	ds_write_b32 v54, v38
	ds_write_b32 v55, v39
	ds_write_b32 v56, v40
	ds_write_b32 v57, v41
	ds_write_b32 v58, v42
	ds_write_b32 v59, v43
	ds_write_b32 v60, v44
	ds_write_b32 v61, v45
	s_mov_b64 s[14:15], 0
	s_lshl_b32 s19, s19, 6
	s_waitcnt lgkmcnt(0)
	s_barrier
; DI unsigned char* WSP(const Params& P) { size_t z = 0; asm volatile("" : "+s"(z)); return P.ws + z; }
; DI unsigned pk2(float a, float b) { f32x2_t v = {a, b}; bf16x2_t r = __builtin_convertvector(v, bf16x2_t); return __builtin_bit_cast(unsigned, r); }
; DI void phase_convert(const Params& P, int l, float* lds) {
;     ...
;     __syncthreads();
;     u16* dst = (u16*)(WSP(P) + WS_W + off);
; #pragma unroll
;     for (int q = 0; q < 2; ++q) {
;       int c = tid + 256 * q, n = c >> 3, k8 = (c & 7) * 8;
;       const float* sp = lds + n * 65 + k8;
;       uint4 v; v.x = pk2(sp[0], sp[1]); v.y = pk2(sp[2], sp[3]); v.z = pk2(sp[4], sp[5]); v.w = pk2(sp[6], sp[7]);
;       *(uint4*)(dst + (long)(nb * 64 + n) * K + kb * 64 + k8) = v;
;     }
;   }
	s_add_u32 s14, s70, s14
	s_addc_u32 s15, s71, s15
	s_add_u32 s14, s14, s44
	s_addc_u32 s15, s15, s45
	s_ashr_i32 s17, s16, 31
	s_lshl_b64 s[12:13], s[16:17], 1
	s_add_u32 s12, s14, s12
	s_addc_u32 s13, s15, s13
	v_lshl_add_u64 v[14:15], s[12:13], 0, v[162:163]
	s_mov_b64 s[12:13], 0x1d100000
	v_lshl_add_u64 v[24:25], v[14:15], 0, s[12:13]
	ds_read2_b32 v[14:15], v21 offset1:1
	ds_read2_b32 v[16:17], v21 offset0:2 offset1:3
	ds_read2_b32 v[26:27], v21 offset0:6 offset1:7
	v_add_u32_e32 v23, s20, v19
	s_waitcnt lgkmcnt(2)
	v_cvt_pk_bf16_f32 v14, v14, v15
	s_waitcnt lgkmcnt(1)
	v_cvt_pk_bf16_f32 v15, v16, v17
	ds_read2_b32 v[16:17], v21 offset0:4 offset1:5
	s_waitcnt lgkmcnt(0)
	v_cvt_pk_bf16_f32 v16, v16, v17
	v_cvt_pk_bf16_f32 v17, v26, v27
	v_mad_i64_i32 v[26:27], s[12:13], v23, s19, 0
	v_lshl_add_u64 v[26:27], v[26:27], 1, v[24:25]
	global_store_dwordx4 v[26:27], v[14:17], off
	ds_read2_b32 v[14:15], v22 offset1:1
	ds_read2_b32 v[16:17], v22 offset0:2 offset1:3
	ds_read2_b32 v[26:27], v22 offset0:6 offset1:7
	v_add_u32_e32 v23, s20, v20
	s_waitcnt lgkmcnt(2)
	v_cvt_pk_bf16_f32 v14, v14, v15
	s_waitcnt lgkmcnt(1)
	v_cvt_pk_bf16_f32 v15, v16, v17
	ds_read2_b32 v[16:17], v22 offset0:4 offset1:5
	s_waitcnt lgkmcnt(0)
	v_cvt_pk_bf16_f32 v16, v16, v17
	v_cvt_pk_bf16_f32 v17, v26, v27
	v_mad_i64_i32 v[26:27], s[12:13], v23, s19, 0
	v_readlane_b32 s12, v247, 3
	s_add_i32 s18, s18, s12
	v_lshl_add_u64 v[24:25], v[26:27], 1, v[24:25]
	s_cmpk_lt_i32 s18, 0x1228
	global_store_dwordx4 v[24:25], v[14:17], off
	s_cbranch_scc1 .LBB0_689
	s_branch .LBB0_768
